# XCD-local grid barrier (no L2 writeback, no cross-XCD round) at the gate/up->down seam and the FFN2-down -> next-layer gate/up seam, guarded by a runtime check that workgroup classes bx%8 each sit on
# speedup vs baseline: 1.0062x; 1.0062x over previous
.LBB0_2:
	s_or_b64 exec, exec, s[4:5]
	v_cmp_eq_u32_e32 vcc, 0, v1
	s_and_saveexec_b64 s[4:5], vcc
	s_cbranch_execz .LBB0_5
	s_add_i32 s0, 0, 0x23500
	v_mov_b32_e32 v2, 0
	v_mov_b32_e32 v3, s0
	s_add_i32 s0, 0, 0x23504
	s_mov_b64 s[8:9], exec
	ds_write_b32 v3, v2
	v_mov_b32_e32 v3, s0
	ds_write_b32 v3, v2
	v_mbcnt_lo_u32_b32 v2, s8, 0
	v_mbcnt_hi_u32_b32 v2, s9, v2
	s_mov_b64 s[10:11], s[84:85]
	v_cmp_eq_u32_e32 vcc, 0, v2
	s_getreg_b32 s0, hwreg(HW_REG_XCC_ID, 0, 4)
	s_and_b64 s[2:3], exec, vcc
	s_mov_b64 exec, s[2:3]
	s_cbranch_execz .LBB0_5
	s_load_dwordx2 s[2:3], s[10:11], 0x110
	s_and_b32 s100, s0, 15
	s_and_b32 s101, s71, 7
	s_lshl_b32 s0, s0, 8
	s_and_b32 s0, s0, 0xf00
	v_mov_b32_e32 v2, 0x4000
	s_waitcnt lgkmcnt(0)
	s_lshl_b32 s101, s101, 3
	s_add_i32 s101, s101, 0x8000
	v_mov_b32_e32 v10, s101
	s_add_i32 s101, s100, 1
	v_mov_b32_e32 v11, s101
	s_sub_i32 s101, 16, s100
	v_mov_b32_e32 v12, s101
	global_atomic_umax v10, v11, s[2:3]
	global_atomic_umax v10, v12, s[2:3] offset:4
	s_add_u32 s0, s2, s0
	s_addc_u32 s1, s3, 0
	s_bcnt1_i32_b64 s2, s[8:9]
	v_mov_b32_e32 v3, s2
	global_atomic_add v2, v3, s[0:1] offset:1024

.LBB0_15:
	s_or_b64 exec, exec, s[4:5]
	s_mov_b64 s[10:11], s[84:85]
	s_barrier
	s_load_dwordx2 s[100:101], s[84:85], 0x110
	v_mbcnt_lo_u32_b32 v10, -1, 0
	v_and_b32_e32 v10, 7, v10
	v_lshlrev_b32_e32 v10, 3, v10
	v_add_u32_e32 v10, 0x8000, v10
	s_waitcnt lgkmcnt(0)
	global_load_dwordx2 v[10:11], v10, s[100:101] sc1
	s_waitcnt vmcnt(0)
	v_add_u32_e32 v10, v10, v11
	v_cmp_ne_u32_e32 vcc, 17, v10
	s_nop 1
	s_cmp_eq_u64 vcc, 0
	s_cselect_b32 s100, 1, 0
	s_nop 0
	v_writelane_b32 v255, s100, 40
	v_mbcnt_lo_u32_b32 v0, -1, 0
	v_mbcnt_hi_u32_b32 v0, -1, v0
	s_getreg_b32 s0, hwreg(HW_REG_HW_ID, 0, 6)
	s_lshl_b32 s0, s0, 2
	s_and_b32 s0, s0, 0xfc
	s_add_i32 s0, s0, 0
	s_add_i32 s0, s0, 0x23400
	v_mov_b32_e32 v1, s0
	ds_read_b32 v1, v1
	s_mov_b32 s1, s71
	v_and_b32_e32 v37, 63, v0
	s_waitcnt lgkmcnt(0)
	v_readfirstlane_b32 s0, v1
	s_nop 1
	v_lshl_add_u32 v1, s0, 6, v0
	s_mov_b32 s0, s72
	v_ashrrev_i32_e32 v1, 6, v1
	s_lshl_b32 s8, s0, 3
	v_lshl_add_u32 v32, s1, 3, v1
	s_mov_b32 s0, 0x9d00
	v_cmp_gt_i32_e32 vcc, s0, v32
	s_and_saveexec_b64 s[12:13], vcc
	s_cbranch_execz .LBB0_74
	s_load_dwordx2 s[0:1], s[10:11], 0x110
	v_lshl_add_u32 v1, v1, 14, 0
	v_and_b32_e32 v2, 7, v0
	v_lshrrev_b32_e32 v34, 3, v37
	v_lshlrev_b32_e32 v36, 2, v2
	s_waitcnt lgkmcnt(0)
	s_add_u32 s14, s0, 0x9d00000
	s_addc_u32 s15, s1, 0
	s_add_u32 s16, s0, 0x9900000
	s_addc_u32 s17, s1, 0
	s_add_u32 s18, s0, 0x8c00000
	s_addc_u32 s19, s1, 0
	s_add_u32 s20, s0, 0x6000000
	v_lshl_add_u32 v33, v2, 4, v1
	v_mul_u32_u24_e32 v3, 0x84, v34
	v_lshlrev_b32_e32 v0, 3, v2
	v_mul_u32_u24_e32 v2, 0x420, v2
	v_lshlrev_b32_e32 v4, 2, v34
	s_addc_u32 s21, s1, 0
	v_mov_b32_e32 v39, 0
	v_add3_u32 v54, v1, v2, v4
	v_or_b32_e32 v1, 32, v34
	s_add_u32 s22, s0, 0x800000
	v_add_u32_e32 v56, v33, v3
	v_or_b32_e32 v51, 8, v34
	v_or_b32_e32 v52, 16, v34
	v_or_b32_e32 v53, 24, v34
	v_mul_u32_u24_e32 v55, 0x84, v1
	s_addc_u32 s23, s1, 0
	v_mov_b32_e32 v35, v39
	s_mov_b64 s[24:25], 0
	s_movk_i32 s9, 0x57ff
	s_mov_b32 s33, 0x83ff
	s_movk_i32 s38, 0xc7f
	s_movk_i32 s39, 0xc80
	s_movk_i32 s40, 0x67f
	s_movk_i32 s41, 0x87f
	s_movk_i32 s42, 0x380
	v_add_u32_e32 v57, 0x420, v56
	v_add_u32_e32 v58, 0x428, v56
	v_add_u32_e32 v59, 0x840, v56
	v_add_u32_e32 v60, 0x848, v56
	v_add_u32_e32 v61, 0xc60, v56
	v_add_u32_e32 v62, 0xc68, v56
	v_add_u32_e32 v63, 0x1080, v56
	v_add_u32_e32 v64, 0x1088, v56
	v_add_u32_e32 v65, 0x14a0, v56
	v_add_u32_e32 v66, 0x14a8, v56
	v_add_u32_e32 v67, 0x18c0, v56
	v_add_u32_e32 v68, 0x18c8, v56
	v_add_u32_e32 v69, 0x1ce0, v56
	v_add_u32_e32 v70, 0x1ce8, v56
	s_movk_i32 s43, 0x4ec5
	s_movk_i32 s44, 0x5f
	s_mov_b32 s45, 0x18000
	s_mov_b32 s46, 0x30000
	s_mov_b32 s47, 0xb00000
	s_mov_b32 s48, 0x580000
	s_mov_b32 s49, 0x8000
	s_mov_b32 s50, 0x10000
	s_mov_b32 s51, 0x20000
	s_mov_b32 s52, 0x28000
	s_mov_b32 s53, 0x38000
	s_mov_b32 s54, 0x2e8ba2e9
	s_movk_i32 s55, 0xff80
	s_mov_b32 s56, 0x16000
	s_mov_b32 s57, 0x2c000
	s_mov_b32 s58, 0x42000
	s_mov_b32 s59, 0x58000
	s_mov_b32 s60, 0x6e000
	s_mov_b32 s61, 0x9cff
	v_mov_b32_e32 v71, 0x100
	v_mov_b32_e32 v72, 0xf8
	v_mov_b32_e32 v73, 0x400000
	v_lshlrev_b32_e32 v40, 2, v36
	v_lshlrev_b32_e32 v42, 1, v0
	v_mov_b32_e32 v74, 0x200000
	v_mov_b32_e32 v75, 0xc08000
	v_mov_b32_e32 v76, 0x2000
	v_mov_b32_e32 v77, 0x680000
	v_mov_b32_e32 v78, 0x48
	v_mov_b32_e32 v79, 5
	v_mov_b32_e32 v80, 4
	v_mov_b32_e32 v81, 6
	v_mov_b32_e32 v82, v32
	s_branch .LBB0_19

.LBB0_1139:
	s_andn2_saveexec_b64 s[2:3], s[12:13]
	s_cbranch_execz .LBB0_1172
	s_mov_b64 s[12:13], exec
	v_readlane_b32 s2, v255, 40
	s_nop 0
	s_cmp_lg_u32 s2, 0
	s_cbranch_scc1 .LBB0_1169
	buffer_wbl2 sc1
	s_waitcnt lgkmcnt(0)
	s_waitcnt vmcnt(0)
	v_mbcnt_lo_u32_b32 v0, s12, 0
	v_mbcnt_hi_u32_b32 v0, s13, v0
	v_cmp_eq_u32_e32 vcc, 0, v0
	s_and_saveexec_b64 s[14:15], vcc
	s_cbranch_execz .LBB0_1142
	s_bcnt1_i32_b64 s2, s[12:13]
	v_mov_b32_e32 v3, s2
	global_atomic_add v3, v254, v3, s[6:7] offset:1024 sc0

.LBB0_1344:
	s_mov_b64 s[12:13], exec
	v_readlane_b32 s2, v255, 40
	s_and_b64 vcc, exec, s[10:11]
	s_cselect_b32 s3, 1, 0
	s_and_b32 s2, s2, s3
	s_cmp_lg_u32 s2, 0
	s_cbranch_scc1 .LBB0_1373
	buffer_wbl2 sc1
	s_waitcnt lgkmcnt(0)
	s_waitcnt vmcnt(0)
	v_mbcnt_lo_u32_b32 v0, s12, 0
	v_mbcnt_hi_u32_b32 v0, s13, v0
	v_cmp_eq_u32_e32 vcc, 0, v0
	s_and_saveexec_b64 s[14:15], vcc
	s_cbranch_execz .LBB0_1346
	s_bcnt1_i32_b64 s2, s[12:13]
	v_mov_b32_e32 v3, s2
	global_atomic_add v3, v254, v3, s[6:7] offset:1024 sc0
